# W2 phase: half of the CUs of each XCD take their context K-slice unit before their latent tile
# speedup vs baseline: 1.0050x; 1.0050x over previous
; #define LAS __attribute__((address_space(3)))
; template <int ONLY>
; __global__ void __launch_bounds__(512, 2) fwd_kernel(Params prm) {
;     ...
;     Frame F;
;     F.P = &prm; F.ws = prm.ws; F.lds = (LAS unsigned char*)lds_raw;
;     F.tid = threadIdx.x; F.lane = F.tid & 63; F.wave = __builtin_amdgcn_readfirstlane(F.tid >> 6);
;     F.G = gridDim.x; F.bid = blockIdx.x; F.vcu = (F.G % 8 == 0) ? (F.bid % 8) * (F.G / 8) + F.bid / 8 : F.bid; F.l = 0;
;     volatile LAS unsigned* MISC = (volatile LAS unsigned*)(F.lds + MISC_OFF);
;     for (int u = F.tid; u < (LDS_BYTES - RING_BYTES) / 4; u += 512) ((LAS unsigned*)(F.lds + RING_BYTES))[u] = 0u;
;     __syncthreads();
;     ...
;     const int lo = 0, hi = N_PHASES;
;     ...
;     const int lo = prm.ph_lo, hi = prm.ph_hi;
;     ...
;     XcdBarrier bar; bar.bar = (unsigned*)(F.ws + WS_CTL) + 4096; bar.x = 0; bar.st = nullptr;
;     if (hi - lo > 1) {
;         bar = xcd_barrier_post((unsigned*)(F.ws + WS_CTL) + 4096, MISC + 8);
;         cg::this_grid().sync();
;         if (threadIdx.x == 0) { unsigned nloc, nx; xcd_barrier_complete(bar.bar, bar.x, nloc, nx); bar.st[0] = nloc; bar.st[1] = nx; }
;         __syncthreads();
;     }
;     const int wave_s = __builtin_amdgcn_readfirstlane(threadIdx.x >> 6);
.LBB0_36:
	s_or_b64 exec, exec, s[2:3]
	s_load_dwordx4 s[4:7], s[62:63], 0xc8
	v_readfirstlane_b32 s0, v1
	s_and_b32 s65, s0, 0xffffffc0
	s_movk_i32 s81, 0xfe
	s_movk_i32 s85, 0x1ff
	s_waitcnt lgkmcnt(0)
	s_add_u32 s0, s6, 0x400000
	v_writelane_b32 v255, s0, 0
	s_addc_u32 s0, s7, 0
	v_writelane_b32 v255, s0, 1
	s_add_u32 s0, s6, 0x100000
	v_writelane_b32 v255, s0, 2
	s_addc_u32 s0, s7, 0
	v_writelane_b32 v255, s0, 3
	s_add_u32 s0, s6, 0x480000
	v_writelane_b32 v255, s0, 4
	s_addc_u32 s0, s7, 0
	v_writelane_b32 v255, s0, 5
	s_add_u32 s0, s6, 0x3e00400
	v_writelane_b32 v255, s0, 6
	s_addc_u32 s0, s7, 0
	v_writelane_b32 v255, s0, 7
	s_add_u32 s0, s6, 0x7400000
	v_writelane_b32 v255, s0, 8
	s_addc_u32 s0, s7, 0
	v_writelane_b32 v255, s0, 9
	s_add_u32 s0, s6, 0x8f00000
	s_addc_u32 s1, s7, 0
	v_writelane_b32 v255, s0, 10
	v_mov_b32_e32 v97, 0
	s_mov_b32 s89, 0x12000
	v_writelane_b32 v255, s1, 11
	s_add_u32 s0, s6, 0x8f02000
	s_addc_u32 s1, s7, 0
	v_writelane_b32 v255, s0, 12
	s_movk_i32 s54, 0x2000
	s_mov_b32 s50, 0x1c000
	v_writelane_b32 v255, s1, 13
	s_add_u32 s0, s6, 0x2600000
	s_addc_u32 s1, s7, 0
	v_writelane_b32 v255, s0, 14
	v_mov_b64_e32 v[178:179], 0x100
	v_mov_b64_e32 v[180:181], 0xff
	v_writelane_b32 v255, s1, 15
	s_add_u32 s0, s6, 0x4c0000
	v_writelane_b32 v255, s0, 16
	v_writelane_b32 v255, s4, 17
	s_addc_u32 s0, s7, 0
	s_add_i32 s2, 0, 0x20160
	v_writelane_b32 v255, s5, 18
	v_writelane_b32 v255, s6, 19
	v_writelane_b32 v255, s7, 20
	v_writelane_b32 v255, s0, 21
	v_writelane_b32 v255, s2, 22
	s_add_i32 s2, 0, 0x20164
	v_writelane_b32 v255, s2, 23
	v_writelane_b32 v255, s62, 24
	s_mov_b32 s51, 0xf800000
	v_mov_b32_e32 v183, 0x260
	v_writelane_b32 v255, s63, 25
	v_writelane_b32 v255, s91, 26
	s_movk_i32 s83, 0x4c80
	s_movk_i32 s49, 0xc00
	s_mov_b32 s69, 0x7f800000
	v_mov_b32_e32 v182, 0xbf1f24be
	v_mov_b32_e32 v184, 0x3e642e9d
	s_movk_i32 s53, 0x204
	s_movk_i32 s33, 0x5ff
	s_brev_b32 s67, 1
	s_mov_b32 s1, 0x47800000
	s_mov_b32 s0, 0x3c000
	s_mov_b32 s90, 0x36000
	v_mov_b32_e32 v185, 0x358637bd
	v_mov_b32_e32 v187, 0x3e91f4c4
	v_mov_b32_e32 v212, 0x3c0881c4
	v_mov_b32_e32 v213, 0xbab64f3b
	v_mov_b32_e32 v254, 0x2000
	v_mov_b32_e32 v217, 0x4000
	v_mov_b32_e32 v216, 0x7fc00000
	v_mov_b32_e32 v218, 0x461c4000
	v_mov_b32_e32 v219, 0x37000000
	v_mov_b32_e32 v220, 0x7f800000
	v_not_b32_e32 v221, 63
	v_not_b32_e32 v222, 31
	v_mov_b32_e32 v223, 0xffc00000
	s_mov_b32 s31, 0x26000
	s_movk_i32 s30, 0x1f8
	s_brev_b32 s29, 18
	s_mov_b32 s92, 0
	s_mov_b32 s101, 0
	v_writelane_b32 v255, s101, 62
	s_mov_b64 s[46:47], 0x80
	s_mov_b32 s52, 0x3a800000
	s_mov_b32 s64, 0x3e75aa41
	s_mov_b32 s66, 0x40490fdb
	s_mov_b32 s68, 0x3d4be544
	s_mov_b64 s[72:73], 0x13200
	s_mov_b64 s[74:75], 0x20000
	s_mov_b64 s[76:77], 0x2000
	s_mov_b64 s[78:79], 0x800000
	s_mov_b32 s80, 0x40234736
	s_mov_b32 s82, 0xc0a55e0e
	s_mov_b32 s84, 0xbfaad1da
	s_mov_b32 s86, 0x4081e0d3
	s_mov_b32 s88, 0xc09de9e6
	s_mov_b32 s17, 0
	v_writelane_b32 v255, s65, 27
	s_barrier
	s_branch .LBB0_40

; #define PG8_STAGE(bufoff, gbase, voff) do { _Pragma("unroll") for (int _i = 0; _i < 2; ++_i) \
;         __builtin_amdgcn_global_load_lds((const unsigned*)((const char*)(gbase) + (voff)[_i]), (LAS unsigned*)(lds + (bufoff) + ldsw + _i * 8192), 16, 0, 0); } while (0)
; #define PG8_WAIT_V(n) asm volatile("s_waitcnt vmcnt(" #n ")" ::: "memory")
; #define PG8_BAR __builtin_amdgcn_s_barrier()
;     ...
;     Unit cur, nxt; int ui = 0;
;     if (!S.next(0, cur)) return;
;     Acc acc;
; #pragma unroll
;     for (int a = 0; a < 2; ++a)
; #pragma unroll
;         for (int b = 0; b < 2; ++b)
; #pragma unroll
;             for (int m = 0; m < 4; ++m)
; #pragma unroll
;                 for (int n = 0; n < 2; ++n) acc[a][b][m][n] = (f32x4){0.f, 0.f, 0.f, 0.f};
;     bf16x8 At[4][2], B0[2][2], B1[2][2];
;     const char* cA = cur.A; const char* cB = cur.B;
;     PG8_STAGE(PG8_SB(0, 0), cB, voffB); PG8_STAGE(PG8_SB(0, 1), cB + hstep, voffB); PG8_STAGE(PG8_SA(0, 0), cA, voffA); PG8_STAGE(PG8_SA(0, 1), cA + hstep, voffA);
;     if (wr == 1) PG8_BAR;
;     PG8_WAIT_V(2); PG8_BAR;
;     PG8_STAGE(PG8_SB(1, 0), cB + kstep, voffB); PG8_STAGE(PG8_SA(1, 0), cA + kstep, voffA); PG8_STAGE(PG8_SB(1, 1), cB + hstep + kstep, voffB);
;     PG8_WAIT_V(6); PG8_BAR;
; DI void phase_g6(const Frame& F) {
;     const unsigned char* W = F.ws + WS_W;
;     {
;         pg8::Sched2 S; S.tileBytes = 256L * 4096 * 2; S.G = F.G; S.c = F.bid;
;         S.j0 = pg8::JobD{(const char*)(F.ws + WS_U), (const char*)(W + W_2), ML / 256, 4, 1, 0, 0}; S.j1 = S.j0; S.n0 = (ML / 256) * 4; S.total = S.n0;
;         EpiRes E{F, 5, false, 1};
;         pg8::gemm_phase(F.lds, 4096, S, E, F.tid);
.Lg6_entry:
	v_readlane_b32 s101, v255, 62
	s_cmp_eq_u32 s101, 2
	s_cbranch_scc1 .Lg6_pre
	s_mov_b32 s101, 0
	v_readlane_b32 s2, v255, 35
	s_cmp_eq_u32 s2, 3
	s_cbranch_scc1 .Lg6_set
	s_bitcmp1_b32 s96, 3
	s_cselect_b32 s101, 1, 0
.Lg6_set:
	v_writelane_b32 v255, s101, 62
.Lg6_pre:
	s_add_u32 s34, s94, 0x2e00000
	s_addc_u32 s35, s95, 0
	s_movk_i32 s2, 0x1000
	v_mov_b32_e32 v12, v224
	s_cmpk_lt_u32 s96, 0x100
	v_and_b32_e32 v0, 0x1ff, v12
	s_cselect_b64 s[4:5], -1, 0
	s_cmpk_gt_u32 s96, 0xff
	v_readfirstlane_b32 s3, v0
	s_cbranch_scc1 .LBB0_68
	v_readlane_b32 s101, v255, 62
	s_cmp_eq_u32 s101, 1
	s_cbranch_scc1 .LBB0_68
	v_lshrrev_b32_e32 v1, 5, v12
	v_lshrrev_b32_e32 v3, 1, v12
	v_and_b32_e32 v1, 4, v1
	v_bfe_u32 v2, v12, 2, 2
	v_and_b32_e32 v16, 24, v3
	s_add_u32 s36, s94, 0xf400000
	v_or3_b32 v1, v1, v2, v16
	v_lshrrev_b32_e32 v2, 3, v0
	v_lshlrev_b32_e32 v0, 4, v0
	v_and_b32_e32 v5, 32, v12
	s_addc_u32 s37, s95, 0
	s_and_b32 s8, s2, 0x1fc0
	v_or_b32_e32 v3, 64, v2
	s_movk_i32 s2, 0x60
	v_bitop3_b32 v13, v0, v5, 48 bitop3:0x6c
	v_and_b32_e32 v14, 64, v12
	v_and_or_b32 v4, v3, s2, v1
	v_or_b32_e32 v0, v13, v14
	v_mul_u32_u24_e32 v4, s8, v4
	v_lshrrev_b32_e32 v0, 1, v0
	v_or_b32_e32 v4, v4, v0
	v_lshlrev_b32_e32 v130, 1, v4
	v_bfe_u32 v4, v12, 2, 4
	s_movk_i32 s2, 0x70
	v_writelane_b32 v255, s4, 37
	v_and_or_b32 v3, v3, s2, v4
	s_lshl_b32 s2, s96, 5
	v_writelane_b32 v255, s5, 38
	s_and_b32 s2, s2, 0xe0
	s_lshr_b32 s4, s96, 3
	s_or_b32 s2, s2, s4
	v_readlane_b32 s4, v255, 30
	s_and_b32 s4, s4, 7
	s_lshl_b32 s5, s4, 3
	s_lshl_b32 s4, s4, 5
	s_sub_i32 s2, s2, s4
	s_bfe_u32 s4, s2, 0x3000d
	s_add_i32 s4, s2, s4
	s_sext_i32_i16 s11, s4
	s_add_i32 s2, s2, s5
	s_and_b32 s5, s11, -8
	s_sub_i32 s2, s2, s5
	s_bfe_u32 s5, s2, 0x60019
	s_add_i32 s5, s2, s5
	s_and_b32 s5, s5, 0xffc0
	s_sub_i32 s2, s2, s5
	s_lshr_b32 s9, s3, 6
	s_bfe_i64 s[6:7], s[2:3], 0x100000
	s_lshr_b32 s10, s3, 8
	s_lshl_b32 s16, s8, 8
	s_lshl_b32 s38, s9, 10
	s_lshr_b32 s4, s11, 3
	s_lshl_b64 s[6:7], s[6:7], 21
	s_add_u32 s26, s36, s6
	s_addc_u32 s27, s37, s7
	s_bfe_i64 s[4:5], s[4:5], 0x100000
	v_and_or_b32 v1, v2, 32, v1
	s_lshl_b64 s[4:5], s[4:5], 21
	v_mul_u32_u24_e32 v1, s8, v1
	s_add_u32 s28, s34, s4
	v_or_b32_e32 v1, v1, v0
	s_addc_u32 s29, s35, s5
	s_add_i32 s39, s38, 0
	v_lshlrev_b32_e32 v134, 1, v1
	s_add_i32 m0, s39, 0x10000
	v_and_or_b32 v1, v2, 48, v4
	global_load_lds_dwordx4 v134, s[28:29]
	s_add_i32 m0, s39, 0x12000
	s_add_u32 s4, s28, s16
	v_mul_u32_u24_e32 v15, s8, v3
	v_mul_u32_u24_e32 v17, s8, v1
	global_load_lds_dwordx4 v130, s[28:29]
	s_addc_u32 s5, s29, 0
	s_add_i32 m0, s39, 0x14000
	v_or_b32_e32 v3, v15, v0
	v_or_b32_e32 v0, v0, v17
	v_mov_b32_e32 v135, v97
	v_mov_b32_e32 v131, v97
	global_load_lds_dwordx4 v134, s[4:5]
	s_add_i32 m0, s39, 0x16000
	s_add_i32 s40, s39, 0x2000
	v_lshlrev_b32_e32 v136, 1, v0
	v_lshl_add_u64 v[4:5], s[4:5], 0, v[134:135]
	v_lshl_add_u64 v[6:7], s[4:5], 0, v[130:131]
	global_load_lds_dwordx4 v130, s[4:5]
	s_mov_b32 m0, s39
	s_add_u32 s4, s26, s16
	s_waitcnt lgkmcnt(0)
	v_lshlrev_b32_e32 v132, 1, v3
	global_load_lds_dwordx4 v136, s[26:27]
	s_mov_b32 m0, s40
	s_addc_u32 s5, s27, 0
	s_add_i32 s41, s39, 0x4000
	global_load_lds_dwordx4 v132, s[26:27]
	s_mov_b32 m0, s41
	s_add_i32 s42, s39, 0x6000
	global_load_lds_dwordx4 v136, s[4:5]
	s_mov_b32 m0, s42
	v_mov_b32_e32 v137, v97
	global_load_lds_dwordx4 v132, s[4:5]
	v_mov_b32_e32 v133, v97
	s_cmp_eq_u32 s10, 1
	s_mov_b32 s61, s70
	v_lshl_add_u64 v[0:1], s[28:29], 0, v[134:135]
	v_lshl_add_u64 v[2:3], s[28:29], 0, v[130:131]
	v_lshl_add_u64 v[8:9], s[26:27], 0, v[136:137]
	v_lshl_add_u64 v[10:11], s[26:27], 0, v[132:133]
	s_cselect_b64 s[70:71], -1, 0
	s_cmp_lg_u32 s10, 1
	s_cbranch_scc1 .LBB0_51
	s_barrier

; DI void phase_g6(const Frame& F) {
;     ...
;     if (F.l < NL - 1) {
;         pg8::Sched2 S; S.tileBytes = 256L * 4096 * 2; S.G = F.G; S.c = F.bid;
;         S.j0 = pg8::JobD{(const char*)(F.ws + WS_U) + (size_t)ML * 4096 * 2, (const char*)(W + W_2), MC / 256, 4, 8, 512 * 2, 512 * 2}; S.j1 = S.j0; S.n0 = (MC / 256) * 4 * 8; S.total = S.n0;
;         EpiSlab E{(float*)(F.ws + WS_KN)};
;         pg8::gemm_phase<4096>(F.lds, 512, S, E, F.tid);
;     }
.LBB0_68:
	v_readlane_b32 s101, v255, 62
	s_cmp_eq_u32 s101, 2
	s_cbranch_scc0 .Lg6_b
	s_mov_b32 s101, 0
	v_writelane_b32 v255, s101, 62
	s_branch .LBB0_87

; DI void phase_g6(const Frame& F) {
;     ...
;     if (F.l < NL - 1) {
;         pg8::Sched2 S; S.tileBytes = 256L * 4096 * 2; S.G = F.G; S.c = F.bid;
;         S.j0 = pg8::JobD{(const char*)(F.ws + WS_U) + (size_t)ML * 4096 * 2, (const char*)(W + W_2), MC / 256, 4, 8, 512 * 2, 512 * 2}; S.j1 = S.j0; S.n0 = (MC / 256) * 4 * 8; S.total = S.n0;
;         EpiSlab E{(float*)(F.ws + WS_KN)};
;         pg8::gemm_phase<4096>(F.lds, 512, S, E, F.tid);
;     }
; }
.LBB0_87:
	v_readlane_b32 s62, v255, 24
	s_mov_b64 s[2:3], 0
	v_readlane_b32 s63, v255, 25
	v_readlane_b32 s101, v255, 62
	s_cmp_eq_u32 s101, 1
	s_cbranch_scc0 .Lg6_end
	s_mov_b32 s101, 2
	v_writelane_b32 v255, s101, 62
	s_branch .Lg6_entry
.Lg6_end:
.LBB0_88:
	v_writelane_b32 v255, s2, 37
	s_nop 1
	v_writelane_b32 v255, s3, 38
	s_branch .LBB0_106
